# merged down phase: no L2 write-back in the up-tail hand-off (its ACT stores are write-through)
# speedup vs baseline: 1.0099x; 1.0058x over previous
.LBB0_3467:
	s_or_b64 exec, exec, s[2:3]
	s_waitcnt lgkmcnt(0)
	s_barrier
	s_waitcnt vmcnt(0)
	s_waitcnt vmcnt(0) lgkmcnt(0)
	s_barrier
	s_and_saveexec_b64 s[2:3], s[0:1]
	s_cbranch_execz .LBB0_3484
	s_mov_b64 s[8:9], exec
	v_mbcnt_lo_u32_b32 v2, s8, 0
	s_add_u32 s4, s6, 0x3700
	v_mbcnt_hi_u32_b32 v2, s9, v2
	s_addc_u32 s5, s7, 0
	v_cmp_eq_u32_e32 vcc, 0, v2
	s_nop 0
	s_and_saveexec_b64 s[10:11], vcc
	s_cbranch_execz .LBB0_3470
	s_bcnt1_i32_b64 s8, s[8:9]
	v_mov_b32_e32 v2, 0
	v_mov_b32_e32 v3, s8
	global_atomic_add v2, v3, s[4:5]
